# v15 + NA loop: the 32 score-register copies moved into the unmasked-tile path only (the masked path overwrites them)
# speedup vs baseline: 1.0060x; 1.0013x over previous
.LBB0_224:
	s_and_saveexec_b64 s[46:47], s[42:43]
	s_cbranch_execz .LBB0_294
	s_bitcmp1_b32 s70, 0
	s_cselect_b32 s42, 0x4600, 0
	v_or_b32_e32 v0, s42, v204
	v_add_u32_e32 v0, v0, v205
	ds_read_b128 v[2:5], v0
	ds_read_b128 v[6:9], v0 offset:4608
	s_setprio 1
	ds_read_b128 v[10:13], v0 offset:32
	ds_read_b128 v[176:179], v0 offset:4640
	s_waitcnt vmcnt(3) lgkmcnt(3)
	v_mfma_f32_32x32x16_bf16 v[64:79], v[2:5], v[80:83], 0
	s_waitcnt lgkmcnt(2)
	v_mfma_f32_32x32x16_bf16 v[48:63], v[6:9], v[80:83], 0
	ds_read_b128 v[2:5], v0 offset:64
	ds_read_b128 v[6:9], v0 offset:4672
	s_waitcnt vmcnt(2) lgkmcnt(3)
	v_mfma_f32_32x32x16_bf16 v[64:79], v[10:13], v[84:87], v[64:79]
	s_waitcnt lgkmcnt(2)
	v_mfma_f32_32x32x16_bf16 v[48:63], v[176:179], v[84:87], v[48:63]
	ds_read_b128 v[10:13], v0 offset:96
	ds_read_b128 v[176:179], v0 offset:4704
	s_waitcnt vmcnt(1) lgkmcnt(3)
	v_mfma_f32_32x32x16_bf16 v[64:79], v[2:5], v[88:91], v[64:79]
	s_waitcnt lgkmcnt(2)
	v_mfma_f32_32x32x16_bf16 v[48:63], v[6:9], v[88:91], v[48:63]
	s_waitcnt vmcnt(0) lgkmcnt(1)
	v_mfma_f32_32x32x16_bf16 v[64:79], v[10:13], v[92:95], v[64:79]
	s_waitcnt lgkmcnt(0)
	v_mfma_f32_32x32x16_bf16 v[48:63], v[176:179], v[92:95], v[48:63]
	v_or_b32_e32 v0, s42, v112
	v_add_u32_e32 v0, v0, v232
	v_add_u32_e32 v155, 0x2000, v0
	v_add_u32_e32 v0, 0x3000, v0
	ds_read2_b64 v[2:5], v155 offset0:128 offset1:130
	ds_read2_b64 v[6:9], v0 offset0:160 offset1:162
	s_mov_b64 s[42:43], -1
	s_and_b64 vcc, exec, s[64:65]
	s_nop 2
	s_cbranch_vccz .LBB0_296
	s_add_i32 s42, s67, s70
	v_cmp_ge_i32_e32 vcc, s42, v145
	v_cmp_lt_i32_e64 s[42:43], s42, v149
	v_mov_b32_e32 v218, 0xff800000
	ds_read2_b32 v[10:11], v153 offset0:0 offset1:1
	ds_read2_b32 v[12:13], v153 offset0:2 offset1:3
	ds_read2_b32 v[14:15], v153 offset0:8 offset1:9
	ds_read2_b32 v[176:177], v153 offset0:10 offset1:11
	ds_read2_b32 v[178:179], v153 offset0:16 offset1:17
	ds_read2_b32 v[180:181], v153 offset0:18 offset1:19
	ds_read2_b32 v[182:183], v153 offset0:24 offset1:25
	ds_read2_b32 v[184:185], v153 offset0:26 offset1:27
	ds_read2_b32 v[186:187], v153 offset0:32 offset1:33
	ds_read2_b32 v[188:189], v153 offset0:34 offset1:35
	ds_read2_b32 v[190:191], v153 offset0:40 offset1:41
	ds_read2_b32 v[192:193], v153 offset0:42 offset1:43
	ds_read2_b32 v[194:195], v153 offset0:48 offset1:49
	ds_read2_b32 v[196:197], v153 offset0:50 offset1:51
	ds_read2_b32 v[198:199], v153 offset0:56 offset1:57
	ds_read2_b32 v[200:201], v153 offset0:58 offset1:59
	s_waitcnt lgkmcnt(0)
	v_fmac_f32_e32 v10, 0x3e38aa3b, v64
	v_fmac_f32_e32 v11, 0x3e38aa3b, v65
	v_fmac_f32_e32 v12, 0x3e38aa3b, v66
	v_fmac_f32_e32 v13, 0x3e38aa3b, v67
	v_fmac_f32_e32 v14, 0x3e38aa3b, v68
	v_fmac_f32_e32 v15, 0x3e38aa3b, v69
	v_fmac_f32_e32 v176, 0x3e38aa3b, v70
	v_fmac_f32_e32 v177, 0x3e38aa3b, v71
	v_fmac_f32_e32 v178, 0x3e38aa3b, v72
	v_fmac_f32_e32 v179, 0x3e38aa3b, v73
	v_fmac_f32_e32 v180, 0x3e38aa3b, v74
	v_fmac_f32_e32 v181, 0x3e38aa3b, v75
	v_fmac_f32_e32 v182, 0x3e38aa3b, v76
	v_fmac_f32_e32 v183, 0x3e38aa3b, v77
	v_fmac_f32_e32 v184, 0x3e38aa3b, v78
	v_fmac_f32_e32 v185, 0x3e38aa3b, v79
	v_fmac_f32_e32 v186, 0x3e38aa3b, v48
	v_fmac_f32_e32 v187, 0x3e38aa3b, v49
	v_fmac_f32_e32 v188, 0x3e38aa3b, v50
	v_fmac_f32_e32 v189, 0x3e38aa3b, v51
	v_fmac_f32_e32 v190, 0x3e38aa3b, v52
	v_fmac_f32_e32 v191, 0x3e38aa3b, v53
	v_fmac_f32_e32 v192, 0x3e38aa3b, v54
	v_fmac_f32_e32 v193, 0x3e38aa3b, v55
	v_fmac_f32_e32 v194, 0x3e38aa3b, v56
	v_fmac_f32_e32 v195, 0x3e38aa3b, v57
	v_fmac_f32_e32 v196, 0x3e38aa3b, v58
	v_fmac_f32_e32 v197, 0x3e38aa3b, v59
	v_fmac_f32_e32 v198, 0x3e38aa3b, v60
	v_fmac_f32_e32 v199, 0x3e38aa3b, v61
	v_fmac_f32_e32 v200, 0x3e38aa3b, v62
	v_fmac_f32_e32 v201, 0x3e38aa3b, v63
	s_and_b64 s[42:43], vcc, s[42:43]
	s_cmp_lg_u32 s32, 0
	s_cbranch_scc1 .Lna_fast
	s_mov_b64 s[100:101], s[42:43]
	s_mov_b64 s[42:43], -1
	v_mov_b32_e32 v221, 0
	v_readlane_b32 s64, v254, 24
	v_readlane_b32 s65, v254, 25
	s_and_b64 s[74:75], s[42:43], s[64:65]
	v_cndmask_b32_e64 v240, 0, 1, s[74:75]
	v_lshl_or_b32 v221, v240, 0, v221
	v_readlane_b32 s64, v254, 26
	v_readlane_b32 s65, v254, 27
	s_and_b64 s[74:75], s[42:43], s[64:65]
	v_cndmask_b32_e64 v240, 0, 1, s[74:75]
	v_lshl_or_b32 v221, v240, 1, v221
	v_readlane_b32 s64, v254, 28
	v_readlane_b32 s65, v254, 29
	s_and_b64 s[74:75], s[42:43], s[64:65]
	v_cndmask_b32_e64 v240, 0, 1, s[74:75]
	v_lshl_or_b32 v221, v240, 2, v221
	v_readlane_b32 s64, v254, 30
	v_readlane_b32 s65, v254, 31
	s_and_b64 s[74:75], s[42:43], s[64:65]
	v_cndmask_b32_e64 v240, 0, 1, s[74:75]
	v_lshl_or_b32 v221, v240, 3, v221
	v_readlane_b32 s64, v254, 32
	v_readlane_b32 s65, v254, 33
	s_and_b64 s[74:75], s[42:43], s[64:65]
	v_cndmask_b32_e64 v240, 0, 1, s[74:75]
	v_lshl_or_b32 v221, v240, 4, v221
	v_readlane_b32 s64, v254, 34
	v_readlane_b32 s65, v254, 35
	s_and_b64 s[74:75], s[42:43], s[64:65]
	v_cndmask_b32_e64 v240, 0, 1, s[74:75]
	v_lshl_or_b32 v221, v240, 5, v221
	v_readlane_b32 s64, v254, 36
	v_readlane_b32 s65, v254, 37
	s_and_b64 s[74:75], s[42:43], s[64:65]
	v_cndmask_b32_e64 v240, 0, 1, s[74:75]
	v_lshl_or_b32 v221, v240, 6, v221
	v_readlane_b32 s64, v254, 38
	v_readlane_b32 s65, v254, 39
	s_and_b64 s[74:75], s[42:43], s[64:65]
	v_cndmask_b32_e64 v240, 0, 1, s[74:75]
	v_lshl_or_b32 v221, v240, 7, v221
	v_readlane_b32 s64, v254, 40
	v_readlane_b32 s65, v254, 41
	v_readlane_b32 s74, v254, 42
	s_and_b64 s[64:65], s[42:43], s[64:65]
	v_readlane_b32 s75, v254, 43
	s_and_b64 s[74:75], s[64:65], s[74:75]
	v_cndmask_b32_e64 v240, 0, 1, s[74:75]
	v_lshl_or_b32 v221, v240, 8, v221
	v_readlane_b32 s64, v254, 44
	v_readlane_b32 s65, v254, 45
	v_readlane_b32 s74, v254, 46
	s_and_b64 s[64:65], s[42:43], s[64:65]
	v_readlane_b32 s75, v254, 47
	s_and_b64 s[74:75], s[64:65], s[74:75]
	v_cndmask_b32_e64 v240, 0, 1, s[74:75]
	v_lshl_or_b32 v221, v240, 9, v221
	v_readlane_b32 s64, v254, 48
	v_readlane_b32 s65, v254, 49
	v_readlane_b32 s74, v254, 50
	s_and_b64 s[64:65], s[42:43], s[64:65]
	v_readlane_b32 s75, v254, 51
	s_and_b64 s[74:75], s[64:65], s[74:75]
	v_cndmask_b32_e64 v240, 0, 1, s[74:75]
	v_lshl_or_b32 v221, v240, 10, v221
	v_readlane_b32 s64, v254, 52
	v_readlane_b32 s65, v254, 53
	v_readlane_b32 s74, v254, 54
	s_and_b64 s[64:65], s[42:43], s[64:65]
	v_readlane_b32 s75, v254, 55
	s_and_b64 s[74:75], s[64:65], s[74:75]
	v_cndmask_b32_e64 v240, 0, 1, s[74:75]
	v_lshl_or_b32 v221, v240, 11, v221
	v_readlane_b32 s64, v254, 56
	v_readlane_b32 s65, v254, 57
	v_readlane_b32 s74, v254, 58
	s_and_b64 s[64:65], s[42:43], s[64:65]
	v_readlane_b32 s75, v254, 59
	s_and_b64 s[74:75], s[64:65], s[74:75]
	v_cndmask_b32_e64 v240, 0, 1, s[74:75]
	v_lshl_or_b32 v221, v240, 12, v221
	v_readlane_b32 s64, v254, 60
	v_readlane_b32 s65, v254, 61
	v_readlane_b32 s74, v254, 62
	s_and_b64 s[64:65], s[42:43], s[64:65]
	v_readlane_b32 s75, v254, 63
	s_and_b64 s[74:75], s[64:65], s[74:75]
	v_cndmask_b32_e64 v240, 0, 1, s[74:75]
	v_lshl_or_b32 v221, v240, 13, v221
	v_readlane_b32 s64, v255, 0
	v_readlane_b32 s65, v255, 1
	v_readlane_b32 s74, v255, 2
	s_and_b64 s[64:65], s[42:43], s[64:65]
	v_readlane_b32 s75, v255, 3
	s_and_b64 s[74:75], s[64:65], s[74:75]
	v_cndmask_b32_e64 v240, 0, 1, s[74:75]
	v_lshl_or_b32 v221, v240, 14, v221
	v_readlane_b32 s64, v255, 4
	v_readlane_b32 s65, v255, 5
	v_readlane_b32 s74, v255, 6
	s_and_b64 s[64:65], s[42:43], s[64:65]
	v_readlane_b32 s75, v255, 7
	s_and_b64 s[74:75], s[64:65], s[74:75]
	v_cndmask_b32_e64 v240, 0, 1, s[74:75]
	v_lshl_or_b32 v221, v240, 15, v221
	v_readlane_b32 s64, v255, 8
	v_readlane_b32 s65, v255, 9
	v_readlane_b32 s74, v255, 10
	s_and_b64 s[64:65], s[42:43], s[64:65]
	v_readlane_b32 s75, v255, 11
	s_and_b64 s[74:75], s[64:65], s[74:75]
	v_cndmask_b32_e64 v240, 0, 1, s[74:75]
	v_lshl_or_b32 v221, v240, 16, v221
	v_readlane_b32 s64, v255, 12
	v_readlane_b32 s65, v255, 13
	s_and_b64 s[64:65], s[42:43], s[64:65]
	s_and_b64 s[74:75], s[64:65], s[94:95]
	v_cndmask_b32_e64 v240, 0, 1, s[74:75]
	v_lshl_or_b32 v221, v240, 17, v221
	s_and_b64 s[64:65], s[42:43], s[96:97]
	s_and_b64 s[74:75], s[64:65], s[40:41]
	v_cndmask_b32_e64 v240, 0, 1, s[74:75]
	v_lshl_or_b32 v221, v240, 18, v221
	s_and_b64 s[64:65], s[42:43], s[4:5]
	s_and_b64 s[74:75], s[64:65], s[6:7]
	v_cndmask_b32_e64 v240, 0, 1, s[74:75]
	v_lshl_or_b32 v221, v240, 19, v221
	s_and_b64 s[64:65], s[42:43], s[8:9]
	s_and_b64 s[74:75], s[64:65], s[10:11]
	v_cndmask_b32_e64 v240, 0, 1, s[74:75]
	v_lshl_or_b32 v221, v240, 20, v221
	s_and_b64 s[64:65], s[42:43], s[12:13]
	s_and_b64 s[74:75], s[64:65], s[14:15]
	v_cndmask_b32_e64 v240, 0, 1, s[74:75]
	v_lshl_or_b32 v221, v240, 21, v221
	s_and_b64 s[64:65], s[42:43], s[16:17]
	s_and_b64 s[74:75], s[64:65], s[18:19]
	v_cndmask_b32_e64 v240, 0, 1, s[74:75]
	v_lshl_or_b32 v221, v240, 22, v221
	s_and_b64 s[64:65], s[42:43], s[20:21]
	s_and_b64 s[74:75], s[64:65], s[22:23]
	v_cndmask_b32_e64 v240, 0, 1, s[74:75]
	v_lshl_or_b32 v221, v240, 23, v221
	s_and_b64 s[74:75], s[42:43], s[24:25]
	v_cndmask_b32_e64 v240, 0, 1, s[74:75]
	v_lshl_or_b32 v221, v240, 24, v221
	s_and_b64 s[74:75], s[42:43], s[26:27]
	v_cndmask_b32_e64 v240, 0, 1, s[74:75]
	v_lshl_or_b32 v221, v240, 25, v221
	s_and_b64 s[74:75], s[42:43], s[28:29]
	v_cndmask_b32_e64 v240, 0, 1, s[74:75]
	v_lshl_or_b32 v221, v240, 26, v221
	s_and_b64 s[74:75], s[42:43], s[30:31]
	v_cndmask_b32_e64 v240, 0, 1, s[74:75]
	v_lshl_or_b32 v221, v240, 27, v221
	s_and_b64 s[74:75], s[42:43], s[34:35]
	v_cndmask_b32_e64 v240, 0, 1, s[74:75]
	v_lshl_or_b32 v221, v240, 28, v221
	s_and_b64 s[74:75], s[42:43], s[36:37]
	v_cndmask_b32_e64 v240, 0, 1, s[74:75]
	v_lshl_or_b32 v221, v240, 29, v221
	s_and_b64 s[74:75], s[42:43], s[0:1]
	v_cndmask_b32_e64 v240, 0, 1, s[74:75]
	v_lshl_or_b32 v221, v240, 30, v221
	s_and_b64 s[64:65], s[42:43], s[38:39]
	v_cndmask_b32_e64 v240, 0, 1, s[64:65]
	v_lshl_or_b32 v221, v240, 31, v221
	s_mov_b64 s[42:43], s[100:101]
	s_mov_b32 s32, 1

.LBB0_296:
	v_mov_b32_e32 v201, v63
	v_mov_b32_e32 v200, v62
	v_mov_b32_e32 v199, v61
	v_mov_b32_e32 v198, v60
	v_mov_b32_e32 v197, v59
	v_mov_b32_e32 v196, v58
	v_mov_b32_e32 v195, v57
	v_mov_b32_e32 v194, v56
	v_mov_b32_e32 v193, v55
	v_mov_b32_e32 v192, v54
	v_mov_b32_e32 v191, v53
	v_mov_b32_e32 v190, v52
	v_mov_b32_e32 v189, v51
	v_mov_b32_e32 v188, v50
	v_mov_b32_e32 v187, v49
	v_mov_b32_e32 v186, v48
	v_mov_b32_e32 v185, v79
	v_mov_b32_e32 v184, v78
	v_mov_b32_e32 v183, v77
	v_mov_b32_e32 v182, v76
	v_mov_b32_e32 v181, v75
	v_mov_b32_e32 v180, v74
	v_mov_b32_e32 v179, v73
	v_mov_b32_e32 v178, v72
	v_mov_b32_e32 v177, v71
	v_mov_b32_e32 v176, v70
	v_mov_b32_e32 v15, v69
	v_mov_b32_e32 v14, v68
	v_mov_b32_e32 v13, v67
	v_mov_b32_e32 v12, v66
	v_mov_b32_e32 v11, v65
	v_mov_b32_e32 v10, v64
	s_and_b64 vcc, exec, s[42:43]
	s_cbranch_vccz .LBB0_291
	v_max3_f32 v64, v64, s55, v65
	v_max3_f32 v64, v64, v66, v67
	v_max3_f32 v64, v64, v68, v69
	v_max3_f32 v64, v64, v70, v71
	v_max3_f32 v64, v64, v72, v73
	v_max3_f32 v64, v64, v74, v75
	v_max3_f32 v64, v64, v76, v77
	v_max3_f32 v64, v64, v78, v79
	v_max3_f32 v48, v64, v48, v49
	v_max3_f32 v48, v48, v50, v51
	v_max3_f32 v48, v48, v52, v53
	v_max3_f32 v48, v48, v54, v55
	v_max3_f32 v48, v48, v56, v57
	v_max3_f32 v48, v48, v58, v59
	v_max3_f32 v48, v48, v60, v61
	v_max3_f32 v48, v48, v62, v63
	v_mov_b32_e32 v49, v48
	s_nop 1
	v_permlane32_swap_b32_e32 v48, v49
	v_max_f32_e32 v49, v49, v49
	v_max_f32_e32 v48, v48, v48
	v_max_f32_e32 v48, v48, v49
	v_mul_f32_e32 v157, 0x3e38aa3b, v48
	v_add_f32_e32 v48, 0x41000000, v174
	v_cmp_gt_f32_e32 vcc, v157, v48
	s_cbranch_vccnz .LBB0_292
	s_branch .LBB0_293
